# attention row sums accumulated with v_pk_add_f32 pairs (8 packed adds per component per tile instead of 16 scalar adds + mov)
# baseline (speedup 1.0000x reference)
.Lattn_unit:
	v_mov_b32_e32 v215, v202
	v_mov_b32_e32 v0, 0
	v_mov_b32_e32 v1, 0
	v_mov_b32_e32 v2, 0
	v_mov_b32_e32 v3, 0
	v_mov_b32_e32 v4, 0
	v_mov_b32_e32 v5, 0
	v_mov_b32_e32 v6, 0
	v_mov_b32_e32 v7, 0
	v_mov_b32_e32 v8, 0
	v_mov_b32_e32 v9, 0
	v_mov_b32_e32 v10, 0
	v_mov_b32_e32 v11, 0
	v_mov_b32_e32 v12, 0
	v_mov_b32_e32 v13, 0
	v_mov_b32_e32 v14, 0
	v_mov_b32_e32 v15, 0
	v_mov_b32_e32 v16, 0
	v_mov_b32_e32 v17, 0
	v_mov_b32_e32 v18, 0
	v_mov_b32_e32 v19, 0
	v_mov_b32_e32 v20, 0
	v_mov_b32_e32 v21, 0
	v_mov_b32_e32 v22, 0
	v_mov_b32_e32 v23, 0
	v_mov_b32_e32 v24, 0
	v_mov_b32_e32 v25, 0
	v_mov_b32_e32 v26, 0
	v_mov_b32_e32 v27, 0
	v_mov_b32_e32 v28, 0
	v_mov_b32_e32 v29, 0
	v_mov_b32_e32 v30, 0
	v_mov_b32_e32 v31, 0
	v_mov_b32_e32 v32, 0
	v_mov_b32_e32 v33, 0
	v_mov_b32_e32 v34, 0
	v_mov_b32_e32 v35, 0
	v_mov_b32_e32 v36, 0
	v_mov_b32_e32 v37, 0
	v_mov_b32_e32 v38, 0
	v_mov_b32_e32 v39, 0
	v_mov_b32_e32 v40, 0
	v_mov_b32_e32 v41, 0
	v_mov_b32_e32 v42, 0
	v_mov_b32_e32 v43, 0
	v_mov_b32_e32 v44, 0
	v_mov_b32_e32 v45, 0
	v_mov_b32_e32 v46, 0
	v_mov_b32_e32 v47, 0
	v_mov_b32_e32 v48, 0
	v_mov_b32_e32 v49, 0
	v_mov_b32_e32 v50, 0
	v_mov_b32_e32 v51, 0
	v_mov_b32_e32 v52, 0
	v_mov_b32_e32 v53, 0
	v_mov_b32_e32 v54, 0
	v_mov_b32_e32 v55, 0
	v_mov_b32_e32 v56, 0
	v_mov_b32_e32 v57, 0
	v_mov_b32_e32 v58, 0
	v_mov_b32_e32 v59, 0
	v_mov_b32_e32 v60, 0
	v_mov_b32_e32 v61, 0
	v_mov_b32_e32 v62, 0
	v_mov_b32_e32 v63, 0
	v_mov_b32_e32 v193, 0
	v_mov_b32_e32 v194, 0
	v_mov_b32_e32 v240, 0
	v_mov_b32_e32 v241, 0
	v_mov_b32_e32 v242, 0
	v_mov_b32_e32 v243, 0
	s_mov_b32 s39, 0
	s_barrier
	s_cmp_lt_u32 s6, 4
	s_cbranch_scc0 .Lattn_halfB

.Lat_nomask6:
	v_exp_f32_e32 v144, v144
	v_exp_f32_e32 v145, v145
	v_exp_f32_e32 v146, v146
	v_pk_add_f32 v[240:241], v[240:241], v[144:145]
	v_exp_f32_e32 v147, v147
	v_mfma_f32_16x16x32_bf16 v[164:167], v[120:123], v[72:75], v[248:251]
	v_cvt_pk_bf16_f32 v176, v144, v145
	v_exp_f32_e32 v148, v148
	ds_read_b128 v[80:83], v233 offset:16384
	v_pk_add_f32 v[240:241], v[240:241], v[146:147]
	v_exp_f32_e32 v149, v149
	v_mfma_f32_16x16x32_bf16 v[164:167], v[124:127], v[76:79], v[164:167]
	v_cvt_pk_bf16_f32 v177, v146, v147
	ds_read_b128 v[84:87], v234 offset:16384
	v_exp_f32_e32 v150, v150
	v_pk_add_f32 v[240:241], v[240:241], v[148:149]
	v_exp_f32_e32 v151, v151
	ds_read_b128 v[88:91], v233 offset:18432
	v_cvt_pk_bf16_f32 v178, v148, v149
	v_mfma_f32_16x16x32_bf16 v[168:171], v[128:131], v[72:75], v[248:251]
	v_exp_f32_e32 v152, v152
	v_pk_add_f32 v[240:241], v[240:241], v[150:151]
	ds_read_b128 v[92:95], v234 offset:18432
	v_exp_f32_e32 v153, v153
	v_cvt_pk_bf16_f32 v179, v150, v151
	v_mfma_f32_16x16x32_bf16 v[168:171], v[132:135], v[76:79], v[168:171]
	v_exp_f32_e32 v154, v154
	ds_read_b128 v[96:99], v233 offset:20480
	v_pk_add_f32 v[240:241], v[240:241], v[152:153]
	v_exp_f32_e32 v155, v155
	v_cvt_pk_bf16_f32 v180, v152, v153
	v_exp_f32_e32 v156, v156
	ds_read_b128 v[100:103], v234 offset:20480
	v_mfma_f32_16x16x32_bf16 v[172:175], v[136:139], v[72:75], v[248:251]
	v_pk_add_f32 v[240:241], v[240:241], v[154:155]
	v_exp_f32_e32 v157, v157
	ds_read_b128 v[104:107], v233 offset:22528
	v_cvt_pk_bf16_f32 v181, v154, v155
	v_exp_f32_e32 v158, v158
	v_mfma_f32_16x16x32_bf16 v[172:175], v[140:143], v[76:79], v[172:175]
	v_pk_add_f32 v[240:241], v[240:241], v[156:157]
	ds_read_b128 v[108:111], v234 offset:22528
	v_exp_f32_e32 v159, v159
	v_cvt_pk_bf16_f32 v182, v156, v157
	v_pk_add_f32 v[240:241], v[240:241], v[158:159]
	v_cvt_pk_bf16_f32 v183, v158, v159
	s_waitcnt lgkmcnt(7)
	ds_read_b128 v[112:115], v233 offset:24576
	ds_read_b128 v[116:119], v234 offset:24576
	ds_read_b128 v[120:123], v233 offset:26624
	ds_read_b128 v[124:127], v234 offset:26624
	ds_read_b128 v[128:131], v233 offset:28672
	ds_read_b128 v[132:135], v234 offset:28672
	ds_read_b128 v[136:139], v233 offset:30720
	ds_read_b128 v[140:143], v234 offset:30720

.Lat_nomask8:
	v_exp_f32_e32 v160, v160
	v_exp_f32_e32 v161, v161
	v_exp_f32_e32 v162, v162
	v_pk_add_f32 v[242:243], v[242:243], v[160:161]
	s_waitcnt lgkmcnt(15)
	v_mfma_f32_16x16x32_bf16 v[0:3], v[80:83], v[176:179], v[0:3]
	v_exp_f32_e32 v163, v163
	v_cvt_pk_bf16_f32 v184, v160, v161
	s_waitcnt lgkmcnt(14)
	v_mfma_f32_16x16x32_bf16 v[0:3], v[84:87], v[180:183], v[0:3]
	v_exp_f32_e32 v164, v164
	s_waitcnt lgkmcnt(13)
	v_mfma_f32_16x16x32_bf16 v[4:7], v[88:91], v[176:179], v[4:7]
	v_pk_add_f32 v[242:243], v[242:243], v[162:163]
	v_exp_f32_e32 v165, v165
	s_waitcnt lgkmcnt(12)
	v_mfma_f32_16x16x32_bf16 v[4:7], v[92:95], v[180:183], v[4:7]
	v_cvt_pk_bf16_f32 v185, v162, v163
	v_exp_f32_e32 v166, v166
	s_waitcnt lgkmcnt(11)
	v_mfma_f32_16x16x32_bf16 v[8:11], v[96:99], v[176:179], v[8:11]
	v_pk_add_f32 v[242:243], v[242:243], v[164:165]
	v_exp_f32_e32 v167, v167
	s_waitcnt lgkmcnt(10)
	v_mfma_f32_16x16x32_bf16 v[8:11], v[100:103], v[180:183], v[8:11]
	v_cvt_pk_bf16_f32 v186, v164, v165
	s_waitcnt lgkmcnt(9)
	v_mfma_f32_16x16x32_bf16 v[12:15], v[104:107], v[176:179], v[12:15]
	v_exp_f32_e32 v168, v168
	v_pk_add_f32 v[242:243], v[242:243], v[166:167]
	s_waitcnt lgkmcnt(8)
	v_mfma_f32_16x16x32_bf16 v[12:15], v[108:111], v[180:183], v[12:15]
	v_exp_f32_e32 v169, v169
	v_cvt_pk_bf16_f32 v187, v166, v167
	s_waitcnt lgkmcnt(7)
	v_mfma_f32_16x16x32_bf16 v[16:19], v[112:115], v[176:179], v[16:19]
	v_exp_f32_e32 v170, v170
	v_pk_add_f32 v[242:243], v[242:243], v[168:169]
	s_waitcnt lgkmcnt(6)
	v_mfma_f32_16x16x32_bf16 v[16:19], v[116:119], v[180:183], v[16:19]
	v_exp_f32_e32 v171, v171
	s_waitcnt lgkmcnt(5)
	v_mfma_f32_16x16x32_bf16 v[20:23], v[120:123], v[176:179], v[20:23]
	v_cvt_pk_bf16_f32 v188, v168, v169
	v_exp_f32_e32 v172, v172
	s_waitcnt lgkmcnt(4)
	v_mfma_f32_16x16x32_bf16 v[20:23], v[124:127], v[180:183], v[20:23]
	v_pk_add_f32 v[242:243], v[242:243], v[170:171]
	v_exp_f32_e32 v173, v173
	s_waitcnt lgkmcnt(3)
	v_mfma_f32_16x16x32_bf16 v[24:27], v[128:131], v[176:179], v[24:27]
	v_cvt_pk_bf16_f32 v189, v170, v171
	v_exp_f32_e32 v174, v174
	s_waitcnt lgkmcnt(2)
	v_mfma_f32_16x16x32_bf16 v[24:27], v[132:135], v[180:183], v[24:27]
	v_pk_add_f32 v[242:243], v[242:243], v[172:173]
	s_waitcnt lgkmcnt(1)
	v_mfma_f32_16x16x32_bf16 v[28:31], v[136:139], v[176:179], v[28:31]
	v_exp_f32_e32 v175, v175
	v_cvt_pk_bf16_f32 v190, v172, v173
	s_waitcnt lgkmcnt(0)
	v_mfma_f32_16x16x32_bf16 v[28:31], v[140:143], v[180:183], v[28:31]
	v_pk_add_f32 v[242:243], v[242:243], v[174:175]
	v_cvt_pk_bf16_f32 v191, v174, v175
	s_nop 1
	v_mfma_f32_16x16x32_bf16 v[32:35], v[80:83], v[184:187], v[32:35]
	v_mfma_f32_16x16x32_bf16 v[32:35], v[84:87], v[188:191], v[32:35]
	v_mfma_f32_16x16x32_bf16 v[36:39], v[88:91], v[184:187], v[36:39]
	v_mfma_f32_16x16x32_bf16 v[36:39], v[92:95], v[188:191], v[36:39]
	v_mfma_f32_16x16x32_bf16 v[40:43], v[96:99], v[184:187], v[40:43]
	v_mfma_f32_16x16x32_bf16 v[40:43], v[100:103], v[188:191], v[40:43]
	v_mfma_f32_16x16x32_bf16 v[44:47], v[104:107], v[184:187], v[44:47]
	v_mfma_f32_16x16x32_bf16 v[44:47], v[108:111], v[188:191], v[44:47]
	v_mfma_f32_16x16x32_bf16 v[48:51], v[112:115], v[184:187], v[48:51]
	v_mfma_f32_16x16x32_bf16 v[48:51], v[116:119], v[188:191], v[48:51]
	v_mfma_f32_16x16x32_bf16 v[52:55], v[120:123], v[184:187], v[52:55]
	v_mfma_f32_16x16x32_bf16 v[52:55], v[124:127], v[188:191], v[52:55]
	v_mfma_f32_16x16x32_bf16 v[56:59], v[128:131], v[184:187], v[56:59]
	v_mfma_f32_16x16x32_bf16 v[56:59], v[132:135], v[188:191], v[56:59]
	v_mfma_f32_16x16x32_bf16 v[60:63], v[136:139], v[184:187], v[60:63]
	v_mfma_f32_16x16x32_bf16 v[60:63], v[140:143], v[188:191], v[60:63]

.Lattn_noNext:
	global_load_dwordx2 v[80:81], v215, s[18:19]
	global_load_dwordx2 v[82:83], v215, s[18:19] offset:32
	global_load_dwordx2 v[84:85], v215, s[18:19] offset:64
	global_load_dwordx2 v[86:87], v215, s[18:19] offset:96
	global_load_dwordx2 v[88:89], v215, s[18:19] offset:128
	global_load_dwordx2 v[90:91], v215, s[18:19] offset:160
	global_load_dwordx2 v[92:93], v215, s[18:19] offset:192
	global_load_dwordx2 v[94:95], v215, s[18:19] offset:224
	global_load_dwordx2 v[96:97], v215, s[28:29]
	global_load_dwordx2 v[112:113], v215, s[14:15]
	global_load_dwordx2 v[128:129], v215, s[16:17]
	global_load_dwordx2 v[98:99], v215, s[28:29] offset:32
	global_load_dwordx2 v[114:115], v215, s[14:15] offset:32
	global_load_dwordx2 v[130:131], v215, s[16:17] offset:32
	global_load_dwordx2 v[100:101], v215, s[28:29] offset:64
	global_load_dwordx2 v[116:117], v215, s[14:15] offset:64
	global_load_dwordx2 v[132:133], v215, s[16:17] offset:64
	global_load_dwordx2 v[102:103], v215, s[28:29] offset:96
	global_load_dwordx2 v[118:119], v215, s[14:15] offset:96
	global_load_dwordx2 v[134:135], v215, s[16:17] offset:96
	global_load_dwordx2 v[104:105], v215, s[28:29] offset:128
	global_load_dwordx2 v[120:121], v215, s[14:15] offset:128
	global_load_dwordx2 v[136:137], v215, s[16:17] offset:128
	global_load_dwordx2 v[106:107], v215, s[28:29] offset:160
	global_load_dwordx2 v[122:123], v215, s[14:15] offset:160
	global_load_dwordx2 v[138:139], v215, s[16:17] offset:160
	global_load_dwordx2 v[108:109], v215, s[28:29] offset:192
	global_load_dwordx2 v[124:125], v215, s[14:15] offset:192
	global_load_dwordx2 v[140:141], v215, s[16:17] offset:192
	global_load_dwordx2 v[110:111], v215, s[28:29] offset:224
	global_load_dwordx2 v[126:127], v215, s[14:15] offset:224
	global_load_dwordx2 v[142:143], v215, s[16:17] offset:224
	global_load_dwordx4 v[144:147], v216, s[4:5]
	global_load_dwordx4 v[148:151], v216, s[4:5] offset:64
	global_load_dwordx4 v[152:155], v216, s[4:5] offset:128
	global_load_dwordx4 v[156:159], v216, s[4:5] offset:192
	global_load_dwordx4 v[160:163], v216, s[4:5] offset:256
	global_load_dwordx4 v[164:167], v216, s[4:5] offset:320
	global_load_dwordx4 v[168:171], v216, s[4:5] offset:384
	global_load_dwordx4 v[172:175], v216, s[4:5] offset:448
	v_add_f32_e32 v193, v240, v241
	v_add_f32_e32 v194, v242, v243
	ds_bpermute_b32 v207, v208, v193
	ds_bpermute_b32 v217, v208, v194
	s_waitcnt lgkmcnt(0)
	v_add_f32_e32 v193, v193, v207
	v_add_f32_e32 v194, v194, v217
	ds_bpermute_b32 v207, v209, v193
	ds_bpermute_b32 v217, v209, v194
	s_waitcnt lgkmcnt(0)
	v_add_f32_e32 v193, v193, v207
	v_add_f32_e32 v194, v194, v217
	v_rcp_f32_e32 v222, v193
	v_rcp_f32_e32 v223, v194
	v_mov_b32_e32 v224, 0
	v_mul_f32_e32 v223, v223, v203
	v_mul_f32_e32 v32, v32, v223
	v_fma_f32 v0, v0, v222, -v32
	v_fmac_f32_e32 v224, v0, v0
	v_mul_f32_e32 v33, v33, v223
	v_fma_f32 v1, v1, v222, -v33
	v_fmac_f32_e32 v224, v1, v1
	v_mul_f32_e32 v34, v34, v223
	v_fma_f32 v2, v2, v222, -v34
	v_fmac_f32_e32 v224, v2, v2
	v_mul_f32_e32 v35, v35, v223
	v_fma_f32 v3, v3, v222, -v35
	v_fmac_f32_e32 v224, v3, v3
	v_mul_f32_e32 v36, v36, v223
	v_fma_f32 v4, v4, v222, -v36
	v_fmac_f32_e32 v224, v4, v4
	v_mul_f32_e32 v37, v37, v223
	v_fma_f32 v5, v5, v222, -v37
	v_fmac_f32_e32 v224, v5, v5
	v_mul_f32_e32 v38, v38, v223
	v_fma_f32 v6, v6, v222, -v38
	v_fmac_f32_e32 v224, v6, v6
	v_mul_f32_e32 v39, v39, v223
	v_fma_f32 v7, v7, v222, -v39
	v_fmac_f32_e32 v224, v7, v7
	v_mul_f32_e32 v40, v40, v223
	v_fma_f32 v8, v8, v222, -v40
	v_fmac_f32_e32 v224, v8, v8
	v_mul_f32_e32 v41, v41, v223
	v_fma_f32 v9, v9, v222, -v41
	v_fmac_f32_e32 v224, v9, v9
	v_mul_f32_e32 v42, v42, v223
	v_fma_f32 v10, v10, v222, -v42
	v_fmac_f32_e32 v224, v10, v10
	v_mul_f32_e32 v43, v43, v223
	v_fma_f32 v11, v11, v222, -v43
	v_fmac_f32_e32 v224, v11, v11
	v_mul_f32_e32 v44, v44, v223
	v_fma_f32 v12, v12, v222, -v44
	v_fmac_f32_e32 v224, v12, v12
	v_mul_f32_e32 v45, v45, v223
	v_fma_f32 v13, v13, v222, -v45
	v_fmac_f32_e32 v224, v13, v13
	v_mul_f32_e32 v46, v46, v223
	v_fma_f32 v14, v14, v222, -v46
	v_fmac_f32_e32 v224, v14, v14
	v_mul_f32_e32 v47, v47, v223
	v_fma_f32 v15, v15, v222, -v47
	v_fmac_f32_e32 v224, v15, v15
	v_mul_f32_e32 v48, v48, v223
	v_fma_f32 v16, v16, v222, -v48
	v_fmac_f32_e32 v224, v16, v16
	v_mul_f32_e32 v49, v49, v223
	v_fma_f32 v17, v17, v222, -v49
	v_fmac_f32_e32 v224, v17, v17
	v_mul_f32_e32 v50, v50, v223
	v_fma_f32 v18, v18, v222, -v50
	v_fmac_f32_e32 v224, v18, v18
	v_mul_f32_e32 v51, v51, v223
	v_fma_f32 v19, v19, v222, -v51
	v_fmac_f32_e32 v224, v19, v19
	v_mul_f32_e32 v52, v52, v223
	v_fma_f32 v20, v20, v222, -v52
	v_fmac_f32_e32 v224, v20, v20
	v_mul_f32_e32 v53, v53, v223
	v_fma_f32 v21, v21, v222, -v53
	v_fmac_f32_e32 v224, v21, v21
	v_mul_f32_e32 v54, v54, v223
	v_fma_f32 v22, v22, v222, -v54
	v_fmac_f32_e32 v224, v22, v22
	v_mul_f32_e32 v55, v55, v223
	v_fma_f32 v23, v23, v222, -v55
	v_fmac_f32_e32 v224, v23, v23
	v_mul_f32_e32 v56, v56, v223
	v_fma_f32 v24, v24, v222, -v56
	v_fmac_f32_e32 v224, v24, v24
	v_mul_f32_e32 v57, v57, v223
	v_fma_f32 v25, v25, v222, -v57
	v_fmac_f32_e32 v224, v25, v25
	v_mul_f32_e32 v58, v58, v223
	v_fma_f32 v26, v26, v222, -v58
	v_fmac_f32_e32 v224, v26, v26
	v_mul_f32_e32 v59, v59, v223
	v_fma_f32 v27, v27, v222, -v59
	v_fmac_f32_e32 v224, v27, v27
	v_mul_f32_e32 v60, v60, v223
	v_fma_f32 v28, v28, v222, -v60
	v_fmac_f32_e32 v224, v28, v28
	v_mul_f32_e32 v61, v61, v223
	v_fma_f32 v29, v29, v222, -v61
	v_fmac_f32_e32 v224, v29, v29
	v_mul_f32_e32 v62, v62, v223
	v_fma_f32 v30, v30, v222, -v62
	v_fmac_f32_e32 v224, v30, v30
	v_mul_f32_e32 v63, v63, v223
	v_fma_f32 v31, v31, v222, -v63
	v_fmac_f32_e32 v224, v31, v31
	global_load_dwordx4 v[32:35], v216, s[88:89]
	global_load_dwordx4 v[36:39], v216, s[88:89] offset:64
	global_load_dwordx4 v[40:43], v216, s[88:89] offset:128
	global_load_dwordx4 v[44:47], v216, s[88:89] offset:192
	global_load_dwordx4 v[48:51], v216, s[88:89] offset:256
	global_load_dwordx4 v[52:55], v216, s[88:89] offset:320
	global_load_dwordx4 v[56:59], v216, s[88:89] offset:384
	global_load_dwordx4 v[60:63], v216, s[88:89] offset:448
	s_waitcnt vmcnt(40)
	v_mov_b32_e32 v225, 0
	v_lshlrev_b32_e32 v207, 16, v80
	v_and_b32_e32 v217, 0xffff0000, v80
	v_fmac_f32_e32 v225, v207, v207
	v_fmac_f32_e32 v225, v217, v217
	v_lshlrev_b32_e32 v207, 16, v81
	v_and_b32_e32 v217, 0xffff0000, v81
	v_fmac_f32_e32 v225, v207, v207
	v_fmac_f32_e32 v225, v217, v217
	v_lshlrev_b32_e32 v207, 16, v82
	v_and_b32_e32 v217, 0xffff0000, v82
	v_fmac_f32_e32 v225, v207, v207
	v_fmac_f32_e32 v225, v217, v217
	v_lshlrev_b32_e32 v207, 16, v83
	v_and_b32_e32 v217, 0xffff0000, v83
	v_fmac_f32_e32 v225, v207, v207
	v_fmac_f32_e32 v225, v217, v217
	v_lshlrev_b32_e32 v207, 16, v84
	v_and_b32_e32 v217, 0xffff0000, v84
	v_fmac_f32_e32 v225, v207, v207
	v_fmac_f32_e32 v225, v217, v217
	v_lshlrev_b32_e32 v207, 16, v85
	v_and_b32_e32 v217, 0xffff0000, v85
	v_fmac_f32_e32 v225, v207, v207
	v_fmac_f32_e32 v225, v217, v217
	v_lshlrev_b32_e32 v207, 16, v86
	v_and_b32_e32 v217, 0xffff0000, v86
	v_fmac_f32_e32 v225, v207, v207
	v_fmac_f32_e32 v225, v217, v217
	v_lshlrev_b32_e32 v207, 16, v87
	v_and_b32_e32 v217, 0xffff0000, v87
	v_fmac_f32_e32 v225, v207, v207
	v_fmac_f32_e32 v225, v217, v217
	v_lshlrev_b32_e32 v207, 16, v88
	v_and_b32_e32 v217, 0xffff0000, v88
	v_fmac_f32_e32 v225, v207, v207
	v_fmac_f32_e32 v225, v217, v217
	v_lshlrev_b32_e32 v207, 16, v89
	v_and_b32_e32 v217, 0xffff0000, v89
	v_fmac_f32_e32 v225, v207, v207
	v_fmac_f32_e32 v225, v217, v217
	v_lshlrev_b32_e32 v207, 16, v90
	v_and_b32_e32 v217, 0xffff0000, v90
	v_fmac_f32_e32 v225, v207, v207
	v_fmac_f32_e32 v225, v217, v217
	v_lshlrev_b32_e32 v207, 16, v91
	v_and_b32_e32 v217, 0xffff0000, v91
	v_fmac_f32_e32 v225, v207, v207
	v_fmac_f32_e32 v225, v217, v217
	v_lshlrev_b32_e32 v207, 16, v92
	v_and_b32_e32 v217, 0xffff0000, v92
	v_fmac_f32_e32 v225, v207, v207
	v_fmac_f32_e32 v225, v217, v217
	v_lshlrev_b32_e32 v207, 16, v93
	v_and_b32_e32 v217, 0xffff0000, v93
	v_fmac_f32_e32 v225, v207, v207
	v_fmac_f32_e32 v225, v217, v217
	v_lshlrev_b32_e32 v207, 16, v94
	v_and_b32_e32 v217, 0xffff0000, v94
	v_fmac_f32_e32 v225, v207, v207
	v_fmac_f32_e32 v225, v217, v217
	v_lshlrev_b32_e32 v207, 16, v95
	v_and_b32_e32 v217, 0xffff0000, v95
	v_fmac_f32_e32 v225, v207, v207
	v_fmac_f32_e32 v225, v217, v217
	ds_bpermute_b32 v207, v208, v224
	ds_bpermute_b32 v217, v208, v225
	s_waitcnt lgkmcnt(0)
	v_add_f32_e32 v224, v224, v207
	v_add_f32_e32 v225, v225, v217
	ds_bpermute_b32 v207, v209, v224
	ds_bpermute_b32 v217, v209, v225
	s_waitcnt lgkmcnt(0)
	v_add_f32_e32 v224, v224, v207
	v_add_f32_e32 v225, v225, v217
	v_mov_b32_e32 v218, 0x358637bd
	v_fmac_f32_e32 v218, 0x3c000000, v224
	v_mov_b32_e32 v219, 0x358637bd
	v_fmac_f32_e32 v219, 0x3c000000, v225
	v_rsq_f32_e32 v226, v218
	v_rsq_f32_e32 v227, v219
	s_nop 0
	v_mul_f32_e32 v226, 0x3f4ccccd, v226
	s_waitcnt vmcnt(0)
	v_lshlrev_b32_e32 v176, 16, v96
	v_lshlrev_b32_e32 v177, 16, v112
	v_lshlrev_b32_e32 v178, 16, v128
	v_lshlrev_b32_e32 v179, 16, v80
	v_mul_f32_e32 v184, 0xbfb8aa3b, v176
	v_mul_f32_e32 v185, 0xbfb8aa3b, v177
	v_mul_f32_e32 v186, 0xbfb8aa3b, v178
	v_exp_f32_e32 v184, v184
	v_exp_f32_e32 v185, v185
	v_exp_f32_e32 v186, v186
	v_mul_f32_e32 v179, v179, v227
	v_add_f32_e32 v184, 1.0, v184
	v_add_f32_e32 v185, 1.0, v185
	v_add_f32_e32 v186, 1.0, v186
	v_rcp_f32_e32 v184, v184
	v_rcp_f32_e32 v185, v185
	v_rcp_f32_e32 v186, v186
	v_mul_f32_e32 v179, v179, v32
	v_mul_f32_e32 v176, v176, v184
	v_mul_f32_e32 v178, v0, v226
	v_mul_f32_e32 v179, v179, v176
	v_mul_f32_e32 v178, v178, v144
	v_mul_f32_e32 v179, v179, v185
	v_fmac_f32_e32 v179, v186, v178
	v_and_b32_e32 v180, 0xffff0000, v96
	v_and_b32_e32 v181, 0xffff0000, v112
	v_and_b32_e32 v182, 0xffff0000, v128
	v_and_b32_e32 v183, 0xffff0000, v80
	v_mul_f32_e32 v187, 0xbfb8aa3b, v180
	v_mul_f32_e32 v188, 0xbfb8aa3b, v181
	v_mul_f32_e32 v189, 0xbfb8aa3b, v182
	v_exp_f32_e32 v187, v187
	v_exp_f32_e32 v188, v188
	v_exp_f32_e32 v189, v189
	v_mul_f32_e32 v183, v183, v227
	v_add_f32_e32 v187, 1.0, v187
	v_add_f32_e32 v188, 1.0, v188
	v_add_f32_e32 v189, 1.0, v189
	v_rcp_f32_e32 v187, v187
	v_rcp_f32_e32 v188, v188
	v_rcp_f32_e32 v189, v189
	v_mul_f32_e32 v183, v183, v33
	v_mul_f32_e32 v180, v180, v187
	v_mul_f32_e32 v182, v1, v226
	v_mul_f32_e32 v183, v183, v180
	v_mul_f32_e32 v182, v182, v145
	v_mul_f32_e32 v183, v183, v188
	v_fmac_f32_e32 v183, v189, v182
	v_cvt_pk_bf16_f32 v190, v179, v183
	v_lshlrev_b32_e32 v176, 16, v97
	v_lshlrev_b32_e32 v177, 16, v113
	v_lshlrev_b32_e32 v178, 16, v129
	v_lshlrev_b32_e32 v179, 16, v81
	v_mul_f32_e32 v184, 0xbfb8aa3b, v176
	v_mul_f32_e32 v185, 0xbfb8aa3b, v177
	v_mul_f32_e32 v186, 0xbfb8aa3b, v178
	v_exp_f32_e32 v184, v184
	v_exp_f32_e32 v185, v185
	v_exp_f32_e32 v186, v186
	v_mul_f32_e32 v179, v179, v227
	v_add_f32_e32 v184, 1.0, v184
	v_add_f32_e32 v185, 1.0, v185
	v_add_f32_e32 v186, 1.0, v186
	v_rcp_f32_e32 v184, v184
	v_rcp_f32_e32 v185, v185
	v_rcp_f32_e32 v186, v186
	v_mul_f32_e32 v179, v179, v34
	v_mul_f32_e32 v176, v176, v184
	v_mul_f32_e32 v178, v2, v226
	v_mul_f32_e32 v179, v179, v176
	v_mul_f32_e32 v178, v178, v146
	v_mul_f32_e32 v179, v179, v185
	v_fmac_f32_e32 v179, v186, v178
	v_and_b32_e32 v180, 0xffff0000, v97
	v_and_b32_e32 v181, 0xffff0000, v113
	v_and_b32_e32 v182, 0xffff0000, v129
	v_and_b32_e32 v183, 0xffff0000, v81
	v_mul_f32_e32 v187, 0xbfb8aa3b, v180
	v_mul_f32_e32 v188, 0xbfb8aa3b, v181
	v_mul_f32_e32 v189, 0xbfb8aa3b, v182
	v_exp_f32_e32 v187, v187
	v_exp_f32_e32 v188, v188
	v_exp_f32_e32 v189, v189
	v_mul_f32_e32 v183, v183, v227
	v_add_f32_e32 v187, 1.0, v187
	v_add_f32_e32 v188, 1.0, v188
	v_add_f32_e32 v189, 1.0, v189
	v_rcp_f32_e32 v187, v187
	v_rcp_f32_e32 v188, v188
	v_rcp_f32_e32 v189, v189
	v_mul_f32_e32 v183, v183, v35
	v_mul_f32_e32 v180, v180, v187
	v_mul_f32_e32 v182, v3, v226
	v_mul_f32_e32 v183, v183, v180
	v_mul_f32_e32 v182, v182, v147
	v_mul_f32_e32 v183, v183, v188
	v_fmac_f32_e32 v183, v189, v182
	v_cvt_pk_bf16_f32 v191, v179, v183
	global_store_dwordx2 v215, v[190:191], s[28:29]
	s_nop 1
	v_lshlrev_b32_e32 v176, 16, v98
	v_lshlrev_b32_e32 v177, 16, v114
	v_lshlrev_b32_e32 v178, 16, v130
	v_lshlrev_b32_e32 v179, 16, v82
	v_mul_f32_e32 v184, 0xbfb8aa3b, v176
	v_mul_f32_e32 v185, 0xbfb8aa3b, v177
	v_mul_f32_e32 v186, 0xbfb8aa3b, v178
	v_exp_f32_e32 v184, v184
	v_exp_f32_e32 v185, v185
	v_exp_f32_e32 v186, v186
	v_mul_f32_e32 v179, v179, v227
	v_add_f32_e32 v184, 1.0, v184
	v_add_f32_e32 v185, 1.0, v185
	v_add_f32_e32 v186, 1.0, v186
	v_rcp_f32_e32 v184, v184
	v_rcp_f32_e32 v185, v185
	v_rcp_f32_e32 v186, v186
	v_mul_f32_e32 v179, v179, v36
	v_mul_f32_e32 v176, v176, v184
	v_mul_f32_e32 v178, v4, v226
	v_mul_f32_e32 v179, v179, v176
	v_mul_f32_e32 v178, v178, v148
	v_mul_f32_e32 v179, v179, v185
	v_fmac_f32_e32 v179, v186, v178
	v_and_b32_e32 v180, 0xffff0000, v98
	v_and_b32_e32 v181, 0xffff0000, v114
	v_and_b32_e32 v182, 0xffff0000, v130
	v_and_b32_e32 v183, 0xffff0000, v82
	v_mul_f32_e32 v187, 0xbfb8aa3b, v180
	v_mul_f32_e32 v188, 0xbfb8aa3b, v181
	v_mul_f32_e32 v189, 0xbfb8aa3b, v182
	v_exp_f32_e32 v187, v187
	v_exp_f32_e32 v188, v188
	v_exp_f32_e32 v189, v189
	v_mul_f32_e32 v183, v183, v227
	v_add_f32_e32 v187, 1.0, v187
	v_add_f32_e32 v188, 1.0, v188
	v_add_f32_e32 v189, 1.0, v189
	v_rcp_f32_e32 v187, v187
	v_rcp_f32_e32 v188, v188
	v_rcp_f32_e32 v189, v189
	v_mul_f32_e32 v183, v183, v37
	v_mul_f32_e32 v180, v180, v187
	v_mul_f32_e32 v182, v5, v226
	v_mul_f32_e32 v183, v183, v180
	v_mul_f32_e32 v182, v182, v149
	v_mul_f32_e32 v183, v183, v188
	v_fmac_f32_e32 v183, v189, v182
	v_cvt_pk_bf16_f32 v190, v179, v183
	v_lshlrev_b32_e32 v176, 16, v99
	v_lshlrev_b32_e32 v177, 16, v115
	v_lshlrev_b32_e32 v178, 16, v131
	v_lshlrev_b32_e32 v179, 16, v83
	v_mul_f32_e32 v184, 0xbfb8aa3b, v176
	v_mul_f32_e32 v185, 0xbfb8aa3b, v177
	v_mul_f32_e32 v186, 0xbfb8aa3b, v178
	v_exp_f32_e32 v184, v184
	v_exp_f32_e32 v185, v185
	v_exp_f32_e32 v186, v186
	v_mul_f32_e32 v179, v179, v227
	v_add_f32_e32 v184, 1.0, v184
	v_add_f32_e32 v185, 1.0, v185
	v_add_f32_e32 v186, 1.0, v186
	v_rcp_f32_e32 v184, v184
	v_rcp_f32_e32 v185, v185
	v_rcp_f32_e32 v186, v186
	v_mul_f32_e32 v179, v179, v38
	v_mul_f32_e32 v176, v176, v184
	v_mul_f32_e32 v178, v6, v226
	v_mul_f32_e32 v179, v179, v176
	v_mul_f32_e32 v178, v178, v150
	v_mul_f32_e32 v179, v179, v185
	v_fmac_f32_e32 v179, v186, v178
	v_and_b32_e32 v180, 0xffff0000, v99
	v_and_b32_e32 v181, 0xffff0000, v115
	v_and_b32_e32 v182, 0xffff0000, v131
	v_and_b32_e32 v183, 0xffff0000, v83
	v_mul_f32_e32 v187, 0xbfb8aa3b, v180
	v_mul_f32_e32 v188, 0xbfb8aa3b, v181
	v_mul_f32_e32 v189, 0xbfb8aa3b, v182
	v_exp_f32_e32 v187, v187
	v_exp_f32_e32 v188, v188
	v_exp_f32_e32 v189, v189
	v_mul_f32_e32 v183, v183, v227
	v_add_f32_e32 v187, 1.0, v187
	v_add_f32_e32 v188, 1.0, v188
	v_add_f32_e32 v189, 1.0, v189
	v_rcp_f32_e32 v187, v187
	v_rcp_f32_e32 v188, v188
	v_rcp_f32_e32 v189, v189
	v_mul_f32_e32 v183, v183, v39
	v_mul_f32_e32 v180, v180, v187
	v_mul_f32_e32 v182, v7, v226
	v_mul_f32_e32 v183, v183, v180
	v_mul_f32_e32 v182, v182, v151
	v_mul_f32_e32 v183, v183, v188
	v_fmac_f32_e32 v183, v189, v182
	v_cvt_pk_bf16_f32 v191, v179, v183
	global_store_dwordx2 v215, v[190:191], s[28:29] offset:32
	s_nop 1
	v_lshlrev_b32_e32 v176, 16, v100
	v_lshlrev_b32_e32 v177, 16, v116
	v_lshlrev_b32_e32 v178, 16, v132
	v_lshlrev_b32_e32 v179, 16, v84
	v_mul_f32_e32 v184, 0xbfb8aa3b, v176
	v_mul_f32_e32 v185, 0xbfb8aa3b, v177
	v_mul_f32_e32 v186, 0xbfb8aa3b, v178
	v_exp_f32_e32 v184, v184
	v_exp_f32_e32 v185, v185
	v_exp_f32_e32 v186, v186
	v_mul_f32_e32 v179, v179, v227
	v_add_f32_e32 v184, 1.0, v184
	v_add_f32_e32 v185, 1.0, v185
	v_add_f32_e32 v186, 1.0, v186
	v_rcp_f32_e32 v184, v184
	v_rcp_f32_e32 v185, v185
	v_rcp_f32_e32 v186, v186
	v_mul_f32_e32 v179, v179, v40
	v_mul_f32_e32 v176, v176, v184
	v_mul_f32_e32 v178, v8, v226
	v_mul_f32_e32 v179, v179, v176
	v_mul_f32_e32 v178, v178, v152
	v_mul_f32_e32 v179, v179, v185
	v_fmac_f32_e32 v179, v186, v178
	v_and_b32_e32 v180, 0xffff0000, v100
	v_and_b32_e32 v181, 0xffff0000, v116
	v_and_b32_e32 v182, 0xffff0000, v132
	v_and_b32_e32 v183, 0xffff0000, v84
	v_mul_f32_e32 v187, 0xbfb8aa3b, v180
	v_mul_f32_e32 v188, 0xbfb8aa3b, v181
	v_mul_f32_e32 v189, 0xbfb8aa3b, v182
	v_exp_f32_e32 v187, v187
	v_exp_f32_e32 v188, v188
	v_exp_f32_e32 v189, v189
	v_mul_f32_e32 v183, v183, v227
	v_add_f32_e32 v187, 1.0, v187
	v_add_f32_e32 v188, 1.0, v188
	v_add_f32_e32 v189, 1.0, v189
	v_rcp_f32_e32 v187, v187
	v_rcp_f32_e32 v188, v188
	v_rcp_f32_e32 v189, v189
	v_mul_f32_e32 v183, v183, v41
	v_mul_f32_e32 v180, v180, v187
	v_mul_f32_e32 v182, v9, v226
	v_mul_f32_e32 v183, v183, v180
	v_mul_f32_e32 v182, v182, v153
	v_mul_f32_e32 v183, v183, v188
	v_fmac_f32_e32 v183, v189, v182
	v_cvt_pk_bf16_f32 v190, v179, v183
	v_lshlrev_b32_e32 v176, 16, v101
	v_lshlrev_b32_e32 v177, 16, v117
	v_lshlrev_b32_e32 v178, 16, v133
	v_lshlrev_b32_e32 v179, 16, v85
	v_mul_f32_e32 v184, 0xbfb8aa3b, v176
	v_mul_f32_e32 v185, 0xbfb8aa3b, v177
	v_mul_f32_e32 v186, 0xbfb8aa3b, v178
	v_exp_f32_e32 v184, v184
	v_exp_f32_e32 v185, v185
	v_exp_f32_e32 v186, v186
	v_mul_f32_e32 v179, v179, v227
	v_add_f32_e32 v184, 1.0, v184
	v_add_f32_e32 v185, 1.0, v185
	v_add_f32_e32 v186, 1.0, v186
	v_rcp_f32_e32 v184, v184
	v_rcp_f32_e32 v185, v185
	v_rcp_f32_e32 v186, v186
	v_mul_f32_e32 v179, v179, v42
	v_mul_f32_e32 v176, v176, v184
	v_mul_f32_e32 v178, v10, v226
	v_mul_f32_e32 v179, v179, v176
	v_mul_f32_e32 v178, v178, v154
	v_mul_f32_e32 v179, v179, v185
	v_fmac_f32_e32 v179, v186, v178
	v_and_b32_e32 v180, 0xffff0000, v101
	v_and_b32_e32 v181, 0xffff0000, v117
	v_and_b32_e32 v182, 0xffff0000, v133
	v_and_b32_e32 v183, 0xffff0000, v85
	v_mul_f32_e32 v187, 0xbfb8aa3b, v180
	v_mul_f32_e32 v188, 0xbfb8aa3b, v181
	v_mul_f32_e32 v189, 0xbfb8aa3b, v182
	v_exp_f32_e32 v187, v187
	v_exp_f32_e32 v188, v188
	v_exp_f32_e32 v189, v189
	v_mul_f32_e32 v183, v183, v227
	v_add_f32_e32 v187, 1.0, v187
	v_add_f32_e32 v188, 1.0, v188
	v_add_f32_e32 v189, 1.0, v189
	v_rcp_f32_e32 v187, v187
	v_rcp_f32_e32 v188, v188
	v_rcp_f32_e32 v189, v189
	v_mul_f32_e32 v183, v183, v43
	v_mul_f32_e32 v180, v180, v187
	v_mul_f32_e32 v182, v11, v226
	v_mul_f32_e32 v183, v183, v180
	v_mul_f32_e32 v182, v182, v155
	v_mul_f32_e32 v183, v183, v188
	v_fmac_f32_e32 v183, v189, v182
	v_cvt_pk_bf16_f32 v191, v179, v183
	global_store_dwordx2 v215, v[190:191], s[28:29] offset:64
	s_nop 1
	v_lshlrev_b32_e32 v176, 16, v102
	v_lshlrev_b32_e32 v177, 16, v118
	v_lshlrev_b32_e32 v178, 16, v134
	v_lshlrev_b32_e32 v179, 16, v86
	v_mul_f32_e32 v184, 0xbfb8aa3b, v176
	v_mul_f32_e32 v185, 0xbfb8aa3b, v177
	v_mul_f32_e32 v186, 0xbfb8aa3b, v178
	v_exp_f32_e32 v184, v184
	v_exp_f32_e32 v185, v185
	v_exp_f32_e32 v186, v186
	v_mul_f32_e32 v179, v179, v227
	v_add_f32_e32 v184, 1.0, v184
	v_add_f32_e32 v185, 1.0, v185
	v_add_f32_e32 v186, 1.0, v186
	v_rcp_f32_e32 v184, v184
	v_rcp_f32_e32 v185, v185
	v_rcp_f32_e32 v186, v186
	v_mul_f32_e32 v179, v179, v44
	v_mul_f32_e32 v176, v176, v184
	v_mul_f32_e32 v178, v12, v226
	v_mul_f32_e32 v179, v179, v176
	v_mul_f32_e32 v178, v178, v156
	v_mul_f32_e32 v179, v179, v185
	v_fmac_f32_e32 v179, v186, v178
	v_and_b32_e32 v180, 0xffff0000, v102
	v_and_b32_e32 v181, 0xffff0000, v118
	v_and_b32_e32 v182, 0xffff0000, v134
	v_and_b32_e32 v183, 0xffff0000, v86
	v_mul_f32_e32 v187, 0xbfb8aa3b, v180
	v_mul_f32_e32 v188, 0xbfb8aa3b, v181
	v_mul_f32_e32 v189, 0xbfb8aa3b, v182
	v_exp_f32_e32 v187, v187
	v_exp_f32_e32 v188, v188
	v_exp_f32_e32 v189, v189
	v_mul_f32_e32 v183, v183, v227
	v_add_f32_e32 v187, 1.0, v187
	v_add_f32_e32 v188, 1.0, v188
	v_add_f32_e32 v189, 1.0, v189
	v_rcp_f32_e32 v187, v187
	v_rcp_f32_e32 v188, v188
	v_rcp_f32_e32 v189, v189
	v_mul_f32_e32 v183, v183, v45
	v_mul_f32_e32 v180, v180, v187
	v_mul_f32_e32 v182, v13, v226
	v_mul_f32_e32 v183, v183, v180
	v_mul_f32_e32 v182, v182, v157
	v_mul_f32_e32 v183, v183, v188
	v_fmac_f32_e32 v183, v189, v182
	v_cvt_pk_bf16_f32 v190, v179, v183
	v_lshlrev_b32_e32 v176, 16, v103
	v_lshlrev_b32_e32 v177, 16, v119
	v_lshlrev_b32_e32 v178, 16, v135
	v_lshlrev_b32_e32 v179, 16, v87
	v_mul_f32_e32 v184, 0xbfb8aa3b, v176
	v_mul_f32_e32 v185, 0xbfb8aa3b, v177
	v_mul_f32_e32 v186, 0xbfb8aa3b, v178
	v_exp_f32_e32 v184, v184
	v_exp_f32_e32 v185, v185
	v_exp_f32_e32 v186, v186
	v_mul_f32_e32 v179, v179, v227
	v_add_f32_e32 v184, 1.0, v184
	v_add_f32_e32 v185, 1.0, v185
	v_add_f32_e32 v186, 1.0, v186
	v_rcp_f32_e32 v184, v184
	v_rcp_f32_e32 v185, v185
	v_rcp_f32_e32 v186, v186
	v_mul_f32_e32 v179, v179, v46
	v_mul_f32_e32 v176, v176, v184
	v_mul_f32_e32 v178, v14, v226
	v_mul_f32_e32 v179, v179, v176
	v_mul_f32_e32 v178, v178, v158
	v_mul_f32_e32 v179, v179, v185
	v_fmac_f32_e32 v179, v186, v178
	v_and_b32_e32 v180, 0xffff0000, v103
	v_and_b32_e32 v181, 0xffff0000, v119
	v_and_b32_e32 v182, 0xffff0000, v135
	v_and_b32_e32 v183, 0xffff0000, v87
	v_mul_f32_e32 v187, 0xbfb8aa3b, v180
	v_mul_f32_e32 v188, 0xbfb8aa3b, v181
	v_mul_f32_e32 v189, 0xbfb8aa3b, v182
	v_exp_f32_e32 v187, v187
	v_exp_f32_e32 v188, v188
	v_exp_f32_e32 v189, v189
	v_mul_f32_e32 v183, v183, v227
	v_add_f32_e32 v187, 1.0, v187
	v_add_f32_e32 v188, 1.0, v188
	v_add_f32_e32 v189, 1.0, v189
	v_rcp_f32_e32 v187, v187
	v_rcp_f32_e32 v188, v188
	v_rcp_f32_e32 v189, v189
	v_mul_f32_e32 v183, v183, v47
	v_mul_f32_e32 v180, v180, v187
	v_mul_f32_e32 v182, v15, v226
	v_mul_f32_e32 v183, v183, v180
	v_mul_f32_e32 v182, v182, v159
	v_mul_f32_e32 v183, v183, v188
	v_fmac_f32_e32 v183, v189, v182
	v_cvt_pk_bf16_f32 v191, v179, v183
	global_store_dwordx2 v215, v[190:191], s[28:29] offset:96
	s_nop 1
	v_lshlrev_b32_e32 v176, 16, v104
	v_lshlrev_b32_e32 v177, 16, v120
	v_lshlrev_b32_e32 v178, 16, v136
	v_lshlrev_b32_e32 v179, 16, v88
	v_mul_f32_e32 v184, 0xbfb8aa3b, v176
	v_mul_f32_e32 v185, 0xbfb8aa3b, v177
	v_mul_f32_e32 v186, 0xbfb8aa3b, v178
	v_exp_f32_e32 v184, v184
	v_exp_f32_e32 v185, v185
	v_exp_f32_e32 v186, v186
	v_mul_f32_e32 v179, v179, v227
	v_add_f32_e32 v184, 1.0, v184
	v_add_f32_e32 v185, 1.0, v185
	v_add_f32_e32 v186, 1.0, v186
	v_rcp_f32_e32 v184, v184
	v_rcp_f32_e32 v185, v185
	v_rcp_f32_e32 v186, v186
	v_mul_f32_e32 v179, v179, v48
	v_mul_f32_e32 v176, v176, v184
	v_mul_f32_e32 v178, v16, v226
	v_mul_f32_e32 v179, v179, v176
	v_mul_f32_e32 v178, v178, v160
	v_mul_f32_e32 v179, v179, v185
	v_fmac_f32_e32 v179, v186, v178
	v_and_b32_e32 v180, 0xffff0000, v104
	v_and_b32_e32 v181, 0xffff0000, v120
	v_and_b32_e32 v182, 0xffff0000, v136
	v_and_b32_e32 v183, 0xffff0000, v88
	v_mul_f32_e32 v187, 0xbfb8aa3b, v180
	v_mul_f32_e32 v188, 0xbfb8aa3b, v181
	v_mul_f32_e32 v189, 0xbfb8aa3b, v182
	v_exp_f32_e32 v187, v187
	v_exp_f32_e32 v188, v188
	v_exp_f32_e32 v189, v189
	v_mul_f32_e32 v183, v183, v227
	v_add_f32_e32 v187, 1.0, v187
	v_add_f32_e32 v188, 1.0, v188
	v_add_f32_e32 v189, 1.0, v189
	v_rcp_f32_e32 v187, v187
	v_rcp_f32_e32 v188, v188
	v_rcp_f32_e32 v189, v189
	v_mul_f32_e32 v183, v183, v49
	v_mul_f32_e32 v180, v180, v187
	v_mul_f32_e32 v182, v17, v226
	v_mul_f32_e32 v183, v183, v180
	v_mul_f32_e32 v182, v182, v161
	v_mul_f32_e32 v183, v183, v188
	v_fmac_f32_e32 v183, v189, v182
	v_cvt_pk_bf16_f32 v190, v179, v183
	v_lshlrev_b32_e32 v176, 16, v105
	v_lshlrev_b32_e32 v177, 16, v121
	v_lshlrev_b32_e32 v178, 16, v137
	v_lshlrev_b32_e32 v179, 16, v89
	v_mul_f32_e32 v184, 0xbfb8aa3b, v176
	v_mul_f32_e32 v185, 0xbfb8aa3b, v177
	v_mul_f32_e32 v186, 0xbfb8aa3b, v178
	v_exp_f32_e32 v184, v184
	v_exp_f32_e32 v185, v185
	v_exp_f32_e32 v186, v186
	v_mul_f32_e32 v179, v179, v227
	v_add_f32_e32 v184, 1.0, v184
	v_add_f32_e32 v185, 1.0, v185
	v_add_f32_e32 v186, 1.0, v186
	v_rcp_f32_e32 v184, v184
	v_rcp_f32_e32 v185, v185
	v_rcp_f32_e32 v186, v186
	v_mul_f32_e32 v179, v179, v50
	v_mul_f32_e32 v176, v176, v184
	v_mul_f32_e32 v178, v18, v226
	v_mul_f32_e32 v179, v179, v176
	v_mul_f32_e32 v178, v178, v162
	v_mul_f32_e32 v179, v179, v185
	v_fmac_f32_e32 v179, v186, v178
	v_and_b32_e32 v180, 0xffff0000, v105
	v_and_b32_e32 v181, 0xffff0000, v121
	v_and_b32_e32 v182, 0xffff0000, v137
	v_and_b32_e32 v183, 0xffff0000, v89
	v_mul_f32_e32 v187, 0xbfb8aa3b, v180
	v_mul_f32_e32 v188, 0xbfb8aa3b, v181
	v_mul_f32_e32 v189, 0xbfb8aa3b, v182
	v_exp_f32_e32 v187, v187
	v_exp_f32_e32 v188, v188
	v_exp_f32_e32 v189, v189
	v_mul_f32_e32 v183, v183, v227
	v_add_f32_e32 v187, 1.0, v187
	v_add_f32_e32 v188, 1.0, v188
	v_add_f32_e32 v189, 1.0, v189
	v_rcp_f32_e32 v187, v187
	v_rcp_f32_e32 v188, v188
	v_rcp_f32_e32 v189, v189
	v_mul_f32_e32 v183, v183, v51
	v_mul_f32_e32 v180, v180, v187
	v_mul_f32_e32 v182, v19, v226
	v_mul_f32_e32 v183, v183, v180
	v_mul_f32_e32 v182, v182, v163
	v_mul_f32_e32 v183, v183, v188
	v_fmac_f32_e32 v183, v189, v182
	v_cvt_pk_bf16_f32 v191, v179, v183
	global_store_dwordx2 v215, v[190:191], s[28:29] offset:128
	s_nop 1
	v_lshlrev_b32_e32 v176, 16, v106
	v_lshlrev_b32_e32 v177, 16, v122
	v_lshlrev_b32_e32 v178, 16, v138
	v_lshlrev_b32_e32 v179, 16, v90
	v_mul_f32_e32 v184, 0xbfb8aa3b, v176
	v_mul_f32_e32 v185, 0xbfb8aa3b, v177
	v_mul_f32_e32 v186, 0xbfb8aa3b, v178
	v_exp_f32_e32 v184, v184
	v_exp_f32_e32 v185, v185
	v_exp_f32_e32 v186, v186
	v_mul_f32_e32 v179, v179, v227
	v_add_f32_e32 v184, 1.0, v184
	v_add_f32_e32 v185, 1.0, v185
	v_add_f32_e32 v186, 1.0, v186
	v_rcp_f32_e32 v184, v184
	v_rcp_f32_e32 v185, v185
	v_rcp_f32_e32 v186, v186
	v_mul_f32_e32 v179, v179, v52
	v_mul_f32_e32 v176, v176, v184
	v_mul_f32_e32 v178, v20, v226
	v_mul_f32_e32 v179, v179, v176
	v_mul_f32_e32 v178, v178, v164
	v_mul_f32_e32 v179, v179, v185
	v_fmac_f32_e32 v179, v186, v178
	v_and_b32_e32 v180, 0xffff0000, v106
	v_and_b32_e32 v181, 0xffff0000, v122
	v_and_b32_e32 v182, 0xffff0000, v138
	v_and_b32_e32 v183, 0xffff0000, v90
	v_mul_f32_e32 v187, 0xbfb8aa3b, v180
	v_mul_f32_e32 v188, 0xbfb8aa3b, v181
	v_mul_f32_e32 v189, 0xbfb8aa3b, v182
	v_exp_f32_e32 v187, v187
	v_exp_f32_e32 v188, v188
	v_exp_f32_e32 v189, v189
	v_mul_f32_e32 v183, v183, v227
	v_add_f32_e32 v187, 1.0, v187
	v_add_f32_e32 v188, 1.0, v188
	v_add_f32_e32 v189, 1.0, v189
	v_rcp_f32_e32 v187, v187
	v_rcp_f32_e32 v188, v188
	v_rcp_f32_e32 v189, v189
	v_mul_f32_e32 v183, v183, v53
	v_mul_f32_e32 v180, v180, v187
	v_mul_f32_e32 v182, v21, v226
	v_mul_f32_e32 v183, v183, v180
	v_mul_f32_e32 v182, v182, v165
	v_mul_f32_e32 v183, v183, v188
	v_fmac_f32_e32 v183, v189, v182
	v_cvt_pk_bf16_f32 v190, v179, v183
	v_lshlrev_b32_e32 v176, 16, v107
	v_lshlrev_b32_e32 v177, 16, v123
	v_lshlrev_b32_e32 v178, 16, v139
	v_lshlrev_b32_e32 v179, 16, v91
	v_mul_f32_e32 v184, 0xbfb8aa3b, v176
	v_mul_f32_e32 v185, 0xbfb8aa3b, v177
	v_mul_f32_e32 v186, 0xbfb8aa3b, v178
	v_exp_f32_e32 v184, v184
	v_exp_f32_e32 v185, v185
	v_exp_f32_e32 v186, v186
	v_mul_f32_e32 v179, v179, v227
	v_add_f32_e32 v184, 1.0, v184
	v_add_f32_e32 v185, 1.0, v185
	v_add_f32_e32 v186, 1.0, v186
	v_rcp_f32_e32 v184, v184
	v_rcp_f32_e32 v185, v185
	v_rcp_f32_e32 v186, v186
	v_mul_f32_e32 v179, v179, v54
	v_mul_f32_e32 v176, v176, v184
	v_mul_f32_e32 v178, v22, v226
	v_mul_f32_e32 v179, v179, v176
	v_mul_f32_e32 v178, v178, v166
	v_mul_f32_e32 v179, v179, v185
	v_fmac_f32_e32 v179, v186, v178
	v_and_b32_e32 v180, 0xffff0000, v107
	v_and_b32_e32 v181, 0xffff0000, v123
	v_and_b32_e32 v182, 0xffff0000, v139
	v_and_b32_e32 v183, 0xffff0000, v91
	v_mul_f32_e32 v187, 0xbfb8aa3b, v180
	v_mul_f32_e32 v188, 0xbfb8aa3b, v181
	v_mul_f32_e32 v189, 0xbfb8aa3b, v182
	v_exp_f32_e32 v187, v187
	v_exp_f32_e32 v188, v188
	v_exp_f32_e32 v189, v189
	v_mul_f32_e32 v183, v183, v227
	v_add_f32_e32 v187, 1.0, v187
	v_add_f32_e32 v188, 1.0, v188
	v_add_f32_e32 v189, 1.0, v189
	v_rcp_f32_e32 v187, v187
	v_rcp_f32_e32 v188, v188
	v_rcp_f32_e32 v189, v189
	v_mul_f32_e32 v183, v183, v55
	v_mul_f32_e32 v180, v180, v187
	v_mul_f32_e32 v182, v23, v226
	v_mul_f32_e32 v183, v183, v180
	v_mul_f32_e32 v182, v182, v167
	v_mul_f32_e32 v183, v183, v188
	v_fmac_f32_e32 v183, v189, v182
	v_cvt_pk_bf16_f32 v191, v179, v183
	global_store_dwordx2 v215, v[190:191], s[28:29] offset:160
	s_nop 1
	v_lshlrev_b32_e32 v176, 16, v108
	v_lshlrev_b32_e32 v177, 16, v124
	v_lshlrev_b32_e32 v178, 16, v140
	v_lshlrev_b32_e32 v179, 16, v92
	v_mul_f32_e32 v184, 0xbfb8aa3b, v176
	v_mul_f32_e32 v185, 0xbfb8aa3b, v177
	v_mul_f32_e32 v186, 0xbfb8aa3b, v178
	v_exp_f32_e32 v184, v184
	v_exp_f32_e32 v185, v185
	v_exp_f32_e32 v186, v186
	v_mul_f32_e32 v179, v179, v227
	v_add_f32_e32 v184, 1.0, v184
	v_add_f32_e32 v185, 1.0, v185
	v_add_f32_e32 v186, 1.0, v186
	v_rcp_f32_e32 v184, v184
	v_rcp_f32_e32 v185, v185
	v_rcp_f32_e32 v186, v186
	v_mul_f32_e32 v179, v179, v56
	v_mul_f32_e32 v176, v176, v184
	v_mul_f32_e32 v178, v24, v226
	v_mul_f32_e32 v179, v179, v176
	v_mul_f32_e32 v178, v178, v168
	v_mul_f32_e32 v179, v179, v185
	v_fmac_f32_e32 v179, v186, v178
	v_and_b32_e32 v180, 0xffff0000, v108
	v_and_b32_e32 v181, 0xffff0000, v124
	v_and_b32_e32 v182, 0xffff0000, v140
	v_and_b32_e32 v183, 0xffff0000, v92
	v_mul_f32_e32 v187, 0xbfb8aa3b, v180
	v_mul_f32_e32 v188, 0xbfb8aa3b, v181
	v_mul_f32_e32 v189, 0xbfb8aa3b, v182
	v_exp_f32_e32 v187, v187
	v_exp_f32_e32 v188, v188
	v_exp_f32_e32 v189, v189
	v_mul_f32_e32 v183, v183, v227
	v_add_f32_e32 v187, 1.0, v187
	v_add_f32_e32 v188, 1.0, v188
	v_add_f32_e32 v189, 1.0, v189
	v_rcp_f32_e32 v187, v187
	v_rcp_f32_e32 v188, v188
	v_rcp_f32_e32 v189, v189
	v_mul_f32_e32 v183, v183, v57
	v_mul_f32_e32 v180, v180, v187
	v_mul_f32_e32 v182, v25, v226
	v_mul_f32_e32 v183, v183, v180
	v_mul_f32_e32 v182, v182, v169
	v_mul_f32_e32 v183, v183, v188
	v_fmac_f32_e32 v183, v189, v182
	v_cvt_pk_bf16_f32 v190, v179, v183
	v_lshlrev_b32_e32 v176, 16, v109
	v_lshlrev_b32_e32 v177, 16, v125
	v_lshlrev_b32_e32 v178, 16, v141
	v_lshlrev_b32_e32 v179, 16, v93
	v_mul_f32_e32 v184, 0xbfb8aa3b, v176
	v_mul_f32_e32 v185, 0xbfb8aa3b, v177
	v_mul_f32_e32 v186, 0xbfb8aa3b, v178
	v_exp_f32_e32 v184, v184
	v_exp_f32_e32 v185, v185
	v_exp_f32_e32 v186, v186
	v_mul_f32_e32 v179, v179, v227
	v_add_f32_e32 v184, 1.0, v184
	v_add_f32_e32 v185, 1.0, v185
	v_add_f32_e32 v186, 1.0, v186
	v_rcp_f32_e32 v184, v184
	v_rcp_f32_e32 v185, v185
	v_rcp_f32_e32 v186, v186
	v_mul_f32_e32 v179, v179, v58
	v_mul_f32_e32 v176, v176, v184
	v_mul_f32_e32 v178, v26, v226
	v_mul_f32_e32 v179, v179, v176
	v_mul_f32_e32 v178, v178, v170
	v_mul_f32_e32 v179, v179, v185
	v_fmac_f32_e32 v179, v186, v178
	v_and_b32_e32 v180, 0xffff0000, v109
	v_and_b32_e32 v181, 0xffff0000, v125
	v_and_b32_e32 v182, 0xffff0000, v141
	v_and_b32_e32 v183, 0xffff0000, v93
	v_mul_f32_e32 v187, 0xbfb8aa3b, v180
	v_mul_f32_e32 v188, 0xbfb8aa3b, v181
	v_mul_f32_e32 v189, 0xbfb8aa3b, v182
	v_exp_f32_e32 v187, v187
	v_exp_f32_e32 v188, v188
	v_exp_f32_e32 v189, v189
	v_mul_f32_e32 v183, v183, v227
	v_add_f32_e32 v187, 1.0, v187
	v_add_f32_e32 v188, 1.0, v188
	v_add_f32_e32 v189, 1.0, v189
	v_rcp_f32_e32 v187, v187
	v_rcp_f32_e32 v188, v188
	v_rcp_f32_e32 v189, v189
	v_mul_f32_e32 v183, v183, v59
	v_mul_f32_e32 v180, v180, v187
	v_mul_f32_e32 v182, v27, v226
	v_mul_f32_e32 v183, v183, v180
	v_mul_f32_e32 v182, v182, v171
	v_mul_f32_e32 v183, v183, v188
	v_fmac_f32_e32 v183, v189, v182
	v_cvt_pk_bf16_f32 v191, v179, v183
	global_store_dwordx2 v215, v[190:191], s[28:29] offset:192
	s_nop 1
	v_lshlrev_b32_e32 v176, 16, v110
	v_lshlrev_b32_e32 v177, 16, v126
	v_lshlrev_b32_e32 v178, 16, v142
	v_lshlrev_b32_e32 v179, 16, v94
	v_mul_f32_e32 v184, 0xbfb8aa3b, v176
	v_mul_f32_e32 v185, 0xbfb8aa3b, v177
	v_mul_f32_e32 v186, 0xbfb8aa3b, v178
	v_exp_f32_e32 v184, v184
	v_exp_f32_e32 v185, v185
	v_exp_f32_e32 v186, v186
	v_mul_f32_e32 v179, v179, v227
	v_add_f32_e32 v184, 1.0, v184
	v_add_f32_e32 v185, 1.0, v185
	v_add_f32_e32 v186, 1.0, v186
	v_rcp_f32_e32 v184, v184
	v_rcp_f32_e32 v185, v185
	v_rcp_f32_e32 v186, v186
	v_mul_f32_e32 v179, v179, v60
	v_mul_f32_e32 v176, v176, v184
	v_mul_f32_e32 v178, v28, v226
	v_mul_f32_e32 v179, v179, v176
	v_mul_f32_e32 v178, v178, v172
	v_mul_f32_e32 v179, v179, v185
	v_fmac_f32_e32 v179, v186, v178
	v_and_b32_e32 v180, 0xffff0000, v110
	v_and_b32_e32 v181, 0xffff0000, v126
	v_and_b32_e32 v182, 0xffff0000, v142
	v_and_b32_e32 v183, 0xffff0000, v94
	v_mul_f32_e32 v187, 0xbfb8aa3b, v180
	v_mul_f32_e32 v188, 0xbfb8aa3b, v181
	v_mul_f32_e32 v189, 0xbfb8aa3b, v182
	v_exp_f32_e32 v187, v187
	v_exp_f32_e32 v188, v188
	v_exp_f32_e32 v189, v189
	v_mul_f32_e32 v183, v183, v227
	v_add_f32_e32 v187, 1.0, v187
	v_add_f32_e32 v188, 1.0, v188
	v_add_f32_e32 v189, 1.0, v189
	v_rcp_f32_e32 v187, v187
	v_rcp_f32_e32 v188, v188
	v_rcp_f32_e32 v189, v189
	v_mul_f32_e32 v183, v183, v61
	v_mul_f32_e32 v180, v180, v187
	v_mul_f32_e32 v182, v29, v226
	v_mul_f32_e32 v183, v183, v180
	v_mul_f32_e32 v182, v182, v173
	v_mul_f32_e32 v183, v183, v188
	v_fmac_f32_e32 v183, v189, v182
	v_cvt_pk_bf16_f32 v190, v179, v183
	v_lshlrev_b32_e32 v176, 16, v111
	v_lshlrev_b32_e32 v177, 16, v127
	v_lshlrev_b32_e32 v178, 16, v143
	v_lshlrev_b32_e32 v179, 16, v95
	v_mul_f32_e32 v184, 0xbfb8aa3b, v176
	v_mul_f32_e32 v185, 0xbfb8aa3b, v177
	v_mul_f32_e32 v186, 0xbfb8aa3b, v178
	v_exp_f32_e32 v184, v184
	v_exp_f32_e32 v185, v185
	v_exp_f32_e32 v186, v186
	v_mul_f32_e32 v179, v179, v227
	v_add_f32_e32 v184, 1.0, v184
	v_add_f32_e32 v185, 1.0, v185
	v_add_f32_e32 v186, 1.0, v186
	v_rcp_f32_e32 v184, v184
	v_rcp_f32_e32 v185, v185
	v_rcp_f32_e32 v186, v186
	v_mul_f32_e32 v179, v179, v62
	v_mul_f32_e32 v176, v176, v184
	v_mul_f32_e32 v178, v30, v226
	v_mul_f32_e32 v179, v179, v176
	v_mul_f32_e32 v178, v178, v174
	v_mul_f32_e32 v179, v179, v185
	v_fmac_f32_e32 v179, v186, v178
	v_and_b32_e32 v180, 0xffff0000, v111
	v_and_b32_e32 v181, 0xffff0000, v127
	v_and_b32_e32 v182, 0xffff0000, v143
	v_and_b32_e32 v183, 0xffff0000, v95
	v_mul_f32_e32 v187, 0xbfb8aa3b, v180
	v_mul_f32_e32 v188, 0xbfb8aa3b, v181
	v_mul_f32_e32 v189, 0xbfb8aa3b, v182
	v_exp_f32_e32 v187, v187
	v_exp_f32_e32 v188, v188
	v_exp_f32_e32 v189, v189
	v_mul_f32_e32 v183, v183, v227
	v_add_f32_e32 v187, 1.0, v187
	v_add_f32_e32 v188, 1.0, v188
	v_add_f32_e32 v189, 1.0, v189
	v_rcp_f32_e32 v187, v187
	v_rcp_f32_e32 v188, v188
	v_rcp_f32_e32 v189, v189
	v_mul_f32_e32 v183, v183, v63
	v_mul_f32_e32 v180, v180, v187
	v_mul_f32_e32 v182, v31, v226
	v_mul_f32_e32 v183, v183, v180
	v_mul_f32_e32 v182, v182, v175
	v_mul_f32_e32 v183, v183, v188
	v_fmac_f32_e32 v183, v189, v182
	v_cvt_pk_bf16_f32 v191, v179, v183
	global_store_dwordx2 v215, v[190:191], s[28:29] offset:224
	s_nop 1
	s_cmp_lg_u32 s90, 0
	s_cbranch_scc1 .Lattn_unit
	s_branch .LBB0_812
